# combine_pass gate matvec: 16 weight rows in flight per round trip instead of 1 (serialized global loads removed)
# speedup vs baseline: 1.0778x; 1.0184x over previous
.Lgate_loop:
	v_lshl_add_u64 v[248:249], v[2:3], 0, s[38:39]
	v_lshl_add_u64 v[248:249], v[248:249], 0, s[38:39]
	v_lshl_add_u64 v[198:199], v[248:249], 0, s[38:39]
	v_lshl_add_u64 v[198:199], v[198:199], 0, s[38:39]
	global_load_dwordx4 v[136:139], v[2:3], off offset:-2048
	global_load_dwordx4 v[140:143], v[2:3], off offset:-1024
	global_load_dwordx4 v[144:147], v[2:3], off
	global_load_dwordx4 v[148:151], v[2:3], off offset:1024
	global_load_dwordx4 v[152:155], v[2:3], off offset:2048
	global_load_dwordx4 v[156:159], v[2:3], off offset:3072
	global_load_dwordx4 v[160:163], v[248:249], off offset:-4096
	global_load_dwordx4 v[164:167], v[248:249], off offset:-3072
	global_load_dwordx4 v[168:171], v[248:249], off offset:-2048
	global_load_dwordx4 v[204:207], v[248:249], off offset:-1024
	global_load_dwordx4 v[212:215], v[248:249], off
	global_load_dwordx4 v[216:219], v[248:249], off offset:1024
	global_load_dwordx4 v[220:223], v[248:249], off offset:2048
	global_load_dwordx4 v[224:227], v[248:249], off offset:3072
	global_load_dwordx4 v[228:231], v[198:199], off offset:-4096
	global_load_dwordx4 v[232:235], v[198:199], off offset:-3072
	v_add_u32_e32 v0, s6, v33
	ds_read_b128 v[8:11], v0
	ds_read_b128 v[12:15], v0 offset:256
	ds_read_b128 v[236:239], v0 offset:512
	v_mov_b64_e32 v[2:3], v[198:199]
	s_add_i32 s6, s6, 64
	ds_read_b128 v[240:243], v0 offset:16
	ds_read_b128 v[244:247], v0 offset:272
	ds_read_b128 v[184:187], v0 offset:528
	s_waitcnt vmcnt(12)
	s_waitcnt lgkmcnt(3)
	v_pk_fma_f32 v[76:77], v[8:9], v[136:137], v[76:77] op_sel_hi:[0,1,1]
	v_pk_fma_f32 v[74:75], v[8:9], v[138:139], v[74:75] op_sel_hi:[0,1,1]
	v_pk_fma_f32 v[70:71], v[12:13], v[136:137], v[70:71] op_sel_hi:[0,1,1]
	v_pk_fma_f32 v[68:69], v[12:13], v[138:139], v[68:69] op_sel_hi:[0,1,1]
	v_pk_fma_f32 v[60:61], v[236:237], v[136:137], v[60:61] op_sel_hi:[0,1,1]
	v_pk_fma_f32 v[58:59], v[236:237], v[138:139], v[58:59] op_sel_hi:[0,1,1]
	v_pk_fma_f32 v[76:77], v[8:9], v[140:141], v[76:77] op_sel:[1,0,0]
	v_pk_fma_f32 v[74:75], v[8:9], v[142:143], v[74:75] op_sel:[1,0,0]
	v_pk_fma_f32 v[70:71], v[12:13], v[140:141], v[70:71] op_sel:[1,0,0]
	v_pk_fma_f32 v[68:69], v[12:13], v[142:143], v[68:69] op_sel:[1,0,0]
	v_pk_fma_f32 v[60:61], v[236:237], v[140:141], v[60:61] op_sel:[1,0,0]
	v_pk_fma_f32 v[58:59], v[236:237], v[142:143], v[58:59] op_sel:[1,0,0]
	v_pk_fma_f32 v[76:77], v[10:11], v[144:145], v[76:77] op_sel_hi:[0,1,1]
	v_pk_fma_f32 v[74:75], v[10:11], v[146:147], v[74:75] op_sel_hi:[0,1,1]
	v_pk_fma_f32 v[70:71], v[14:15], v[144:145], v[70:71] op_sel_hi:[0,1,1]
	v_pk_fma_f32 v[68:69], v[14:15], v[146:147], v[68:69] op_sel_hi:[0,1,1]
	v_pk_fma_f32 v[60:61], v[238:239], v[144:145], v[60:61] op_sel_hi:[0,1,1]
	v_pk_fma_f32 v[58:59], v[238:239], v[146:147], v[58:59] op_sel_hi:[0,1,1]
	v_pk_fma_f32 v[76:77], v[10:11], v[148:149], v[76:77] op_sel:[1,0,0]
	v_pk_fma_f32 v[74:75], v[10:11], v[150:151], v[74:75] op_sel:[1,0,0]
	v_pk_fma_f32 v[70:71], v[14:15], v[148:149], v[70:71] op_sel:[1,0,0]
	v_pk_fma_f32 v[68:69], v[14:15], v[150:151], v[68:69] op_sel:[1,0,0]
	v_pk_fma_f32 v[60:61], v[238:239], v[148:149], v[60:61] op_sel:[1,0,0]
	v_pk_fma_f32 v[58:59], v[238:239], v[150:151], v[58:59] op_sel:[1,0,0]
	ds_read_b128 v[8:11], v0 offset:32
	ds_read_b128 v[12:15], v0 offset:288
	ds_read_b128 v[236:239], v0 offset:544
	s_waitcnt vmcnt(8)
	s_waitcnt lgkmcnt(3)
	v_pk_fma_f32 v[76:77], v[240:241], v[152:153], v[76:77] op_sel_hi:[0,1,1]
	v_pk_fma_f32 v[74:75], v[240:241], v[154:155], v[74:75] op_sel_hi:[0,1,1]
	v_pk_fma_f32 v[70:71], v[244:245], v[152:153], v[70:71] op_sel_hi:[0,1,1]
	v_pk_fma_f32 v[68:69], v[244:245], v[154:155], v[68:69] op_sel_hi:[0,1,1]
	v_pk_fma_f32 v[60:61], v[184:185], v[152:153], v[60:61] op_sel_hi:[0,1,1]
	v_pk_fma_f32 v[58:59], v[184:185], v[154:155], v[58:59] op_sel_hi:[0,1,1]
	v_pk_fma_f32 v[76:77], v[240:241], v[156:157], v[76:77] op_sel:[1,0,0]
	v_pk_fma_f32 v[74:75], v[240:241], v[158:159], v[74:75] op_sel:[1,0,0]
	v_pk_fma_f32 v[70:71], v[244:245], v[156:157], v[70:71] op_sel:[1,0,0]
	v_pk_fma_f32 v[68:69], v[244:245], v[158:159], v[68:69] op_sel:[1,0,0]
	v_pk_fma_f32 v[60:61], v[184:185], v[156:157], v[60:61] op_sel:[1,0,0]
	v_pk_fma_f32 v[58:59], v[184:185], v[158:159], v[58:59] op_sel:[1,0,0]
	v_pk_fma_f32 v[76:77], v[242:243], v[160:161], v[76:77] op_sel_hi:[0,1,1]
	v_pk_fma_f32 v[74:75], v[242:243], v[162:163], v[74:75] op_sel_hi:[0,1,1]
	v_pk_fma_f32 v[70:71], v[246:247], v[160:161], v[70:71] op_sel_hi:[0,1,1]
	v_pk_fma_f32 v[68:69], v[246:247], v[162:163], v[68:69] op_sel_hi:[0,1,1]
	v_pk_fma_f32 v[60:61], v[186:187], v[160:161], v[60:61] op_sel_hi:[0,1,1]
	v_pk_fma_f32 v[58:59], v[186:187], v[162:163], v[58:59] op_sel_hi:[0,1,1]
	v_pk_fma_f32 v[76:77], v[242:243], v[164:165], v[76:77] op_sel:[1,0,0]
	v_pk_fma_f32 v[74:75], v[242:243], v[166:167], v[74:75] op_sel:[1,0,0]
	v_pk_fma_f32 v[70:71], v[246:247], v[164:165], v[70:71] op_sel:[1,0,0]
	v_pk_fma_f32 v[68:69], v[246:247], v[166:167], v[68:69] op_sel:[1,0,0]
	v_pk_fma_f32 v[60:61], v[186:187], v[164:165], v[60:61] op_sel:[1,0,0]
	v_pk_fma_f32 v[58:59], v[186:187], v[166:167], v[58:59] op_sel:[1,0,0]
	ds_read_b128 v[240:243], v0 offset:48
	ds_read_b128 v[244:247], v0 offset:304
	ds_read_b128 v[184:187], v0 offset:560
	s_waitcnt vmcnt(4)
	s_waitcnt lgkmcnt(3)
	v_pk_fma_f32 v[76:77], v[8:9], v[168:169], v[76:77] op_sel_hi:[0,1,1]
	v_pk_fma_f32 v[74:75], v[8:9], v[170:171], v[74:75] op_sel_hi:[0,1,1]
	v_pk_fma_f32 v[70:71], v[12:13], v[168:169], v[70:71] op_sel_hi:[0,1,1]
	v_pk_fma_f32 v[68:69], v[12:13], v[170:171], v[68:69] op_sel_hi:[0,1,1]
	v_pk_fma_f32 v[60:61], v[236:237], v[168:169], v[60:61] op_sel_hi:[0,1,1]
	v_pk_fma_f32 v[58:59], v[236:237], v[170:171], v[58:59] op_sel_hi:[0,1,1]
	v_pk_fma_f32 v[76:77], v[8:9], v[204:205], v[76:77] op_sel:[1,0,0]
	v_pk_fma_f32 v[74:75], v[8:9], v[206:207], v[74:75] op_sel:[1,0,0]
	v_pk_fma_f32 v[70:71], v[12:13], v[204:205], v[70:71] op_sel:[1,0,0]
	v_pk_fma_f32 v[68:69], v[12:13], v[206:207], v[68:69] op_sel:[1,0,0]
	v_pk_fma_f32 v[60:61], v[236:237], v[204:205], v[60:61] op_sel:[1,0,0]
	v_pk_fma_f32 v[58:59], v[236:237], v[206:207], v[58:59] op_sel:[1,0,0]
	v_pk_fma_f32 v[76:77], v[10:11], v[212:213], v[76:77] op_sel_hi:[0,1,1]
	v_pk_fma_f32 v[74:75], v[10:11], v[214:215], v[74:75] op_sel_hi:[0,1,1]
	v_pk_fma_f32 v[70:71], v[14:15], v[212:213], v[70:71] op_sel_hi:[0,1,1]
	v_pk_fma_f32 v[68:69], v[14:15], v[214:215], v[68:69] op_sel_hi:[0,1,1]
	v_pk_fma_f32 v[60:61], v[238:239], v[212:213], v[60:61] op_sel_hi:[0,1,1]
	v_pk_fma_f32 v[58:59], v[238:239], v[214:215], v[58:59] op_sel_hi:[0,1,1]
	v_pk_fma_f32 v[76:77], v[10:11], v[216:217], v[76:77] op_sel:[1,0,0]
	v_pk_fma_f32 v[74:75], v[10:11], v[218:219], v[74:75] op_sel:[1,0,0]
	v_pk_fma_f32 v[70:71], v[14:15], v[216:217], v[70:71] op_sel:[1,0,0]
	v_pk_fma_f32 v[68:69], v[14:15], v[218:219], v[68:69] op_sel:[1,0,0]
	v_pk_fma_f32 v[60:61], v[238:239], v[216:217], v[60:61] op_sel:[1,0,0]
	v_pk_fma_f32 v[58:59], v[238:239], v[218:219], v[58:59] op_sel:[1,0,0]
	s_waitcnt vmcnt(0)
	s_waitcnt lgkmcnt(0)
	v_pk_fma_f32 v[76:77], v[240:241], v[220:221], v[76:77] op_sel_hi:[0,1,1]
	v_pk_fma_f32 v[74:75], v[240:241], v[222:223], v[74:75] op_sel_hi:[0,1,1]
	v_pk_fma_f32 v[70:71], v[244:245], v[220:221], v[70:71] op_sel_hi:[0,1,1]
	v_pk_fma_f32 v[68:69], v[244:245], v[222:223], v[68:69] op_sel_hi:[0,1,1]
	v_pk_fma_f32 v[60:61], v[184:185], v[220:221], v[60:61] op_sel_hi:[0,1,1]
	v_pk_fma_f32 v[58:59], v[184:185], v[222:223], v[58:59] op_sel_hi:[0,1,1]
	v_pk_fma_f32 v[76:77], v[240:241], v[224:225], v[76:77] op_sel:[1,0,0]
	v_pk_fma_f32 v[74:75], v[240:241], v[226:227], v[74:75] op_sel:[1,0,0]
	v_pk_fma_f32 v[70:71], v[244:245], v[224:225], v[70:71] op_sel:[1,0,0]
	v_pk_fma_f32 v[68:69], v[244:245], v[226:227], v[68:69] op_sel:[1,0,0]
	v_pk_fma_f32 v[60:61], v[184:185], v[224:225], v[60:61] op_sel:[1,0,0]
	v_pk_fma_f32 v[58:59], v[184:185], v[226:227], v[58:59] op_sel:[1,0,0]
	v_pk_fma_f32 v[76:77], v[242:243], v[228:229], v[76:77] op_sel_hi:[0,1,1]
	v_pk_fma_f32 v[74:75], v[242:243], v[230:231], v[74:75] op_sel_hi:[0,1,1]
	v_pk_fma_f32 v[70:71], v[246:247], v[228:229], v[70:71] op_sel_hi:[0,1,1]
	v_pk_fma_f32 v[68:69], v[246:247], v[230:231], v[68:69] op_sel_hi:[0,1,1]
	v_pk_fma_f32 v[60:61], v[186:187], v[228:229], v[60:61] op_sel_hi:[0,1,1]
	v_pk_fma_f32 v[58:59], v[186:187], v[230:231], v[58:59] op_sel_hi:[0,1,1]
	v_pk_fma_f32 v[76:77], v[242:243], v[232:233], v[76:77] op_sel:[1,0,0]
	v_pk_fma_f32 v[74:75], v[242:243], v[234:235], v[74:75] op_sel:[1,0,0]
	v_pk_fma_f32 v[70:71], v[246:247], v[232:233], v[70:71] op_sel:[1,0,0]
	v_pk_fma_f32 v[68:69], v[246:247], v[234:235], v[68:69] op_sel:[1,0,0]
	v_pk_fma_f32 v[60:61], v[186:187], v[232:233], v[60:61] op_sel:[1,0,0]
	v_pk_fma_f32 v[58:59], v[186:187], v[234:235], v[58:59] op_sel:[1,0,0]
	s_cmpk_lg_i32 s6, 0x100
	s_cbranch_scc1 .Lgate_loop
	v_swap_b32 v77, v74
	v_swap_b32 v71, v68
	v_swap_b32 v61, v58
	v_cmp_gt_i32_e32 vcc, s11, v18
	v_lshlrev_b32_e32 v35, 2, v32
	v_lshlrev_b32_e32 v72, 1, v20
	v_lshlrev_b32_e32 v66, 1, v34
	s_and_saveexec_b64 s[14:15], vcc
	s_cbranch_execz .LBB0_1226
	v_ashrrev_i32_e32 v19, 31, v18
	v_lshlrev_b64 v[2:3], 9, v[18:19]
	v_lshl_add_u64 v[4:5], v[28:29], 0, v[2:3]
	v_lshl_add_u64 v[2:3], v[30:31], 0, v[2:3]
	global_load_dwordx2 v[8:9], v[4:5], off
	global_load_dwordx2 v[10:11], v[2:3], off
	v_mov_b64_e32 v[6:7], s[56:57]
	v_mad_i64_i32 v[80:81], s[6:7], v18, s24, v[6:7]
	v_mov_b32_e32 v73, v1
	s_load_dwordx2 s[6:7], s[52:53], 0xc8
	v_lshl_add_u64 v[2:3], v[80:81], 0, v[72:73]
	s_movk_i32 s2, 0x1000
	v_add_co_u32_e32 v2, vcc, s2, v2
	v_readlane_b32 s2, v255, 55
	v_readlane_b32 s3, v255, 56
	s_lshl_b64 s[12:13], s[2:3], 2
	s_waitcnt lgkmcnt(0)
	s_add_u32 s6, s6, s12
	v_addc_co_u32_e32 v3, vcc, 0, v3, vcc
	s_addc_u32 s7, s7, s13
	global_load_dwordx2 v[12:13], v[2:3], off offset:512
	v_add_u32_e32 v73, -1, v18
	global_load_dwordx4 v[2:5], v35, s[6:7]
	v_mov_b32_e32 v67, v1
	v_mad_i64_i32 v[88:89], s[6:7], v73, s24, v[6:7]
	v_lshl_add_u64 v[6:7], v[80:81], 0, v[66:67]
	global_load_dwordx2 v[86:87], v[6:7], off
	v_cmp_lt_i32_e64 s[44:45], v188, v182
	v_cmp_gt_i32_e32 vcc, s93, v18
	v_mov_b32_e32 v82, 0
	v_cndmask_b32_e64 v14, v181, v188, s[44:45]
	v_cmp_lt_i32_e64 s[44:45], v191, v182
	v_lshlrev_b32_e32 v65, 2, v14
	v_cndmask_b32_e32 v0, v252, v202, vcc
	v_cndmask_b32_e64 v15, v181, v191, s[44:45]
	v_lshlrev_b32_e32 v63, 2, v15
	v_lshlrev_b64 v[14:15], 11, v[18:19]
	v_cmp_lt_i32_e64 s[44:45], v190, v182
	v_lshl_add_u64 v[78:79], v[52:53], 0, v[14:15]
	v_and_b32_e32 v0, v0, v18
	v_cndmask_b32_e64 v16, v181, v190, s[44:45]
	v_cmp_lt_i32_e64 s[44:45], v189, v182
	v_lshlrev_b32_e32 v43, 2, v16
	v_mov_b32_e32 v84, 0
	v_cndmask_b32_e64 v17, v181, v189, s[44:45]
	v_lshlrev_b32_e32 v39, 2, v17
	v_cmp_ne_u32_e64 s[44:45], 0, v0
	s_waitcnt vmcnt(4)
	v_lshlrev_b32_e32 v7, 16, v9
	v_lshlrev_b32_e32 v6, 16, v8
	s_waitcnt vmcnt(3)
	v_lshlrev_b32_e32 v15, 16, v11
	v_lshlrev_b32_e32 v14, 16, v10
	v_and_b32_e32 v9, 0xffff0000, v9
	v_and_b32_e32 v8, 0xffff0000, v8
	v_and_b32_e32 v11, 0xffff0000, v11
	v_and_b32_e32 v10, 0xffff0000, v10
	v_pk_add_f32 v[6:7], v[6:7], v[14:15]
	v_pk_add_f32 v[8:9], v[8:9], v[10:11]
	v_mov_b32_e32 v14, v6
	v_mov_b32_e32 v15, v8
	v_mov_b32_e32 v16, v9
	v_mov_b32_e32 v17, v7
	v_pk_mul_f32 v[14:15], v[14:15], v[14:15]
	v_pk_mul_f32 v[16:17], v[16:17], v[16:17]
	v_add_f32_e32 v14, v14, v15
	v_add_f32_e32 v14, v14, v17
	v_add_f32_e32 v14, v16, v14
	ds_bpermute_b32 v15, v65, v14
	s_waitcnt vmcnt(2)
	v_lshlrev_b32_e32 v11, 16, v13
	v_lshlrev_b32_e32 v10, 16, v12
	v_and_b32_e32 v13, 0xffff0000, v13
	v_and_b32_e32 v12, 0xffff0000, v12
	s_waitcnt lgkmcnt(0)
	v_add_f32_e32 v85, v14, v15
	ds_bpermute_b32 v90, v63, v85
	s_waitcnt vmcnt(1)
	v_mov_b32_e32 v14, v2
	v_mov_b32_e32 v15, v4
	v_mul_f32_e32 v73, 0xbfb8aa3b, v10
	v_mul_f32_e32 v83, 0xbfb8aa3b, v12
	s_waitcnt lgkmcnt(0)
	v_add_f32_e32 v2, v85, v90
	ds_bpermute_b32 v4, v43, v2
	v_mul_f32_e32 v16, 0xbfb8aa3b, v11
	v_mul_f32_e32 v17, 0xbfb8aa3b, v13
	v_exp_f32_e32 v73, v73
	v_exp_f32_e32 v83, v83
	s_waitcnt lgkmcnt(0)
	v_add_f32_e32 v2, v2, v4
	ds_bpermute_b32 v4, v39, v2
	v_exp_f32_e32 v16, v16
	v_exp_f32_e32 v17, v17
	v_add_f32_e32 v73, 1.0, v73
	v_add_f32_e32 v83, 1.0, v83
	s_waitcnt lgkmcnt(0)
	v_add_f32_e32 v2, v2, v4
	v_fmamk_f32 v2, v2, 0x3c800000, v174
	v_mul_f32_e32 v4, 0x4b800000, v2
	v_cmp_gt_f32_e64 s[46:47], s27, v2
	v_add_f32_e32 v85, 1.0, v16
	v_add_f32_e32 v91, 1.0, v17
	v_cndmask_b32_e64 v2, v2, v4, s[46:47]
	v_rcp_f32_e32 v16, v73
	v_rcp_f32_e32 v90, v83
	v_rcp_f32_e32 v17, v85
	v_rcp_f32_e32 v91, v91
	v_rsq_f32_e32 v73, v2
	v_mov_b32_e32 v4, v3
	v_pk_mul_f32 v[2:3], v[16:17], v[10:11]
	v_pk_mul_f32 v[10:11], v[90:91], v[12:13]
	v_mul_f32_e32 v12, 0x45800000, v73
	v_cndmask_b32_e64 v12, v73, v12, s[46:47]
	v_pk_mul_f32 v[8:9], v[8:9], v[12:13] op_sel_hi:[1,0]
	v_pk_mul_f32 v[6:7], v[6:7], v[12:13] op_sel_hi:[1,0]
	v_pk_mul_f32 v[4:5], v[4:5], v[8:9]
	v_pk_mul_f32 v[6:7], v[14:15], v[6:7]
	v_pk_mul_f32 v[4:5], v[10:11], v[4:5]
	v_pk_mul_f32 v[2:3], v[2:3], v[6:7]
	v_and_b32_sdwa v8, v5, v177 dst_sel:DWORD dst_unused:UNUSED_PAD src0_sel:WORD_1 src1_sel:DWORD
	v_and_b32_sdwa v9, v4, v177 dst_sel:DWORD dst_unused:UNUSED_PAD src0_sel:WORD_1 src1_sel:DWORD
	v_and_b32_sdwa v6, v3, v177 dst_sel:DWORD dst_unused:UNUSED_PAD src0_sel:WORD_1 src1_sel:DWORD
	v_and_b32_sdwa v7, v2, v177 dst_sel:DWORD dst_unused:UNUSED_PAD src0_sel:WORD_1 src1_sel:DWORD
	v_add3_u32 v5, v5, v8, s28
	v_add3_u32 v4, v4, v9, s28
	v_add3_u32 v2, v2, v7, s28
	v_add3_u32 v3, v3, v6, s28
	v_and_b32_e32 v5, 0xffff0000, v5
	v_and_b32_e32 v4, 0xffff0000, v4
	v_or_b32_sdwa v3, v5, v3 dst_sel:DWORD dst_unused:UNUSED_PAD src0_sel:DWORD src1_sel:WORD_1
	v_or_b32_sdwa v2, v4, v2 dst_sel:DWORD dst_unused:UNUSED_PAD src0_sel:DWORD src1_sel:WORD_1
	v_mov_b32_e32 v85, 0
	global_store_dwordx2 v[78:79], v[2:3], off offset:1024
	s_and_saveexec_b64 s[16:17], s[44:45]
	s_cbranch_execz .LBB0_1214
	v_lshl_add_u64 v[2:3], v[88:89], 0, v[66:67]
	global_load_dwordx2 v[84:85], v[2:3], off
